# attention output stores (MLA, MoBA): 8 x dwordx2 per lane replaced by 4 x dwordx4 via v_permlane32_swap
# speedup vs baseline: 1.0112x; 1.0009x over previous
; DI unsigned pk2(float lo, float hi) { f32x2 v = {lo, hi}; bf16x2_t b = __builtin_convertvector(v, bf16x2_t); return __builtin_bit_cast(unsigned, b); }
; template <int MODE>
; DI void attn_unit(unsigned char* ws, int b, int h, int qb, LAS unsigned char* lds, bool do_store = true) {
;     ...
;     if (MODE != 1) { const float inv = 1.f / lacc[0];
; #pragma unroll
;         for (int i = 0; i < 16; ++i) { o0[i] *= inv; o1[i] *= inv; } }
;     bf16_t* orow = Ob + (size_t)(rowbase + qg) * OPITCH + ocol + 4 * hh;
;     if (do_store)
; #pragma unroll
;     for (int g = 0; g < 4; ++g) {
;         u32x2 a, c; a.x = pk2(o0[4 * g], o0[4 * g + 1]); a.y = pk2(o0[4 * g + 2], o0[4 * g + 3]); c.x = pk2(o1[4 * g], o1[4 * g + 1]); c.y = pk2(o1[4 * g + 2], o1[4 * g + 3]);
;         *(u32x2*)(orow + 8 * g) = a; *(u32x2*)(orow + 32 + 8 * g) = c;
;     }
.LBB0_94:
	v_div_scale_f32 v0, s[14:15], v48, v48, 1.0
	v_rcp_f32_e32 v2, v0
	v_div_scale_f32 v3, vcc, 1.0, v48, 1.0
	s_mov_b32 s49, s3
	v_fma_f32 v4, -v0, v2, 1.0
	v_fmac_f32_e32 v2, v4, v2
	v_mul_f32_e32 v4, v3, v2
	v_fma_f32 v5, -v0, v4, v3
	v_fmac_f32_e32 v4, v5, v2
	v_fma_f32 v0, -v0, v4, v3
	v_div_fmas_f32 v0, v0, v2, v4
	v_div_fixup_f32 v0, v0, v48, 1.0
	v_pk_mul_f32 v[4:5], v[0:1], v[16:17] op_sel_hi:[0,1]
	v_pk_mul_f32 v[16:17], v[0:1], v[30:31] op_sel_hi:[0,1]
	v_lshlrev_b64 v[30:31], 10, v[176:177]
	v_lshl_add_u64 v[30:31], s[28:29], 0, v[30:31]
	v_pk_mul_f32 v[2:3], v[0:1], v[32:33] op_sel_hi:[0,1]
	v_pk_mul_f32 v[6:7], v[0:1], v[34:35] op_sel_hi:[0,1]
	v_pk_mul_f32 v[8:9], v[0:1], v[18:19] op_sel_hi:[0,1]
	v_pk_mul_f32 v[10:11], v[0:1], v[36:37] op_sel_hi:[0,1]
	v_pk_mul_f32 v[12:13], v[0:1], v[20:21] op_sel_hi:[0,1]
	v_pk_mul_f32 v[14:15], v[0:1], v[38:39] op_sel_hi:[0,1]
	v_pk_mul_f32 v[18:19], v[0:1], v[22:23] op_sel_hi:[0,1]
	v_pk_mul_f32 v[20:21], v[0:1], v[40:41] op_sel_hi:[0,1]
	v_pk_mul_f32 v[22:23], v[0:1], v[24:25] op_sel_hi:[0,1]
	v_pk_mul_f32 v[24:25], v[0:1], v[42:43] op_sel_hi:[0,1]
	v_pk_mul_f32 v[26:27], v[0:1], v[26:27] op_sel_hi:[0,1]
	v_pk_mul_f32 v[32:33], v[0:1], v[44:45] op_sel_hi:[0,1]
	v_pk_mul_f32 v[28:29], v[0:1], v[28:29] op_sel_hi:[0,1]
	v_pk_mul_f32 v[36:37], v[0:1], v[46:47] op_sel_hi:[0,1]
	v_lshl_add_u64 v[30:31], v[30:31], 0, s[48:49]
	v_lshlrev_b32_e32 v0, 1, v179
	v_lshl_add_u64 v[34:35], v[30:31], 0, v[0:1]
	v_cvt_pk_bf16_f32 v236, v2, v3
	v_cvt_pk_bf16_f32 v237, v6, v7
	v_cvt_pk_bf16_f32 v238, v10, v11
	v_cvt_pk_bf16_f32 v239, v14, v15
	v_cvt_pk_bf16_f32 v240, v4, v5
	v_cvt_pk_bf16_f32 v241, v8, v9
	v_cvt_pk_bf16_f32 v242, v12, v13
	v_cvt_pk_bf16_f32 v243, v18, v19
	v_cvt_pk_bf16_f32 v244, v20, v21
	v_cvt_pk_bf16_f32 v245, v24, v25
	v_cvt_pk_bf16_f32 v246, v32, v33
	v_cvt_pk_bf16_f32 v247, v36, v37
	v_cvt_pk_bf16_f32 v248, v22, v23
	v_cvt_pk_bf16_f32 v249, v26, v27
	v_cvt_pk_bf16_f32 v250, v28, v29
	v_cvt_pk_bf16_f32 v251, v16, v17
	v_lshrrev_b32_e32 v2, 2, v216
	v_and_b32_e32 v2, 8, v2
	v_add_co_u32_e32 v34, vcc, v2, v34
	s_nop 1
	v_addc_co_u32_e32 v35, vcc, 0, v35, vcc
	s_nop 1
	v_permlane32_swap_b32_e32 v236, v238
	v_permlane32_swap_b32_e32 v237, v239
	v_permlane32_swap_b32_e32 v240, v242
	v_permlane32_swap_b32_e32 v241, v243
	v_permlane32_swap_b32_e32 v244, v246
	v_permlane32_swap_b32_e32 v245, v247
	v_permlane32_swap_b32_e32 v248, v250
	v_permlane32_swap_b32_e32 v249, v251
	global_store_dwordx4 v[34:35], v[236:239], off
	global_store_dwordx4 v[34:35], v[240:243], off offset:64
	global_store_dwordx4 v[34:35], v[244:247], off offset:32
	global_store_dwordx4 v[34:35], v[248:251], off offset:96
	s_mov_b64 s[38:39], 0
	s_branch .LBB0_96

; DI unsigned pk2(float lo, float hi) { f32x2 v = {lo, hi}; bf16x2_t b = __builtin_convertvector(v, bf16x2_t); return __builtin_bit_cast(unsigned, b); }
; template <int MODE>
; DI void attn_unit(unsigned char* ws, int b, int h, int qb, LAS unsigned char* lds, bool do_store = true) {
;     ...
;     if (MODE != 1) { const float inv = 1.f / lacc[0];
; #pragma unroll
;         for (int i = 0; i < 16; ++i) { o0[i] *= inv; o1[i] *= inv; } }
;     bf16_t* orow = Ob + (size_t)(rowbase + qg) * OPITCH + ocol + 4 * hh;
;     if (do_store)
; #pragma unroll
;     for (int g = 0; g < 4; ++g) {
;         u32x2 a, c; a.x = pk2(o0[4 * g], o0[4 * g + 1]); a.y = pk2(o0[4 * g + 2], o0[4 * g + 3]); c.x = pk2(o1[4 * g], o1[4 * g + 1]); c.y = pk2(o1[4 * g + 2], o1[4 * g + 3]);
;         *(u32x2*)(orow + 8 * g) = a; *(u32x2*)(orow + 32 + 8 * g) = c;
;     }
.LBB0_173:
	v_div_scale_f32 v0, s[38:39], v2, v2, 1.0
	v_rcp_f32_e32 v3, v0
	v_div_scale_f32 v4, vcc, 1.0, v2, 1.0
	s_mov_b64 s[38:39], 0
	v_fma_f32 v5, -v0, v3, 1.0
	v_fmac_f32_e32 v3, v5, v3
	v_mul_f32_e32 v5, v4, v3
	v_fma_f32 v6, -v0, v5, v4
	v_fmac_f32_e32 v5, v6, v3
	v_fma_f32 v0, -v0, v5, v4
	v_div_fmas_f32 v0, v0, v3, v5
	v_div_fixup_f32 v0, v0, v2, 1.0
	v_pk_mul_f32 v[2:3], v[0:1], v[34:35] op_sel_hi:[0,1]
	v_pk_mul_f32 v[4:5], v[0:1], v[18:19] op_sel_hi:[0,1]
	v_pk_mul_f32 v[6:7], v[0:1], v[36:37] op_sel_hi:[0,1]
	v_pk_mul_f32 v[8:9], v[0:1], v[20:21] op_sel_hi:[0,1]
	v_pk_mul_f32 v[10:11], v[0:1], v[38:39] op_sel_hi:[0,1]
	v_pk_mul_f32 v[12:13], v[0:1], v[22:23] op_sel_hi:[0,1]
	v_pk_mul_f32 v[14:15], v[0:1], v[40:41] op_sel_hi:[0,1]
	v_pk_mul_f32 v[18:19], v[0:1], v[24:25] op_sel_hi:[0,1]
	v_pk_mul_f32 v[20:21], v[0:1], v[42:43] op_sel_hi:[0,1]
	v_pk_mul_f32 v[22:23], v[0:1], v[26:27] op_sel_hi:[0,1]
	v_pk_mul_f32 v[24:25], v[0:1], v[44:45] op_sel_hi:[0,1]
	v_pk_mul_f32 v[26:27], v[0:1], v[28:29] op_sel_hi:[0,1]
	v_pk_mul_f32 v[28:29], v[0:1], v[46:47] op_sel_hi:[0,1]
	v_pk_mul_f32 v[30:31], v[0:1], v[30:31] op_sel_hi:[0,1]
	v_pk_mul_f32 v[36:37], v[0:1], v[48:49] op_sel_hi:[0,1]
	v_pk_mul_f32 v[16:17], v[0:1], v[32:33] op_sel_hi:[0,1]
	v_lshlrev_b32_e32 v0, 1, v165
	v_lshl_add_u64 v[34:35], v[156:157], 0, v[0:1]
	v_cvt_pk_bf16_f32 v236, v2, v3
	v_cvt_pk_bf16_f32 v237, v6, v7
	v_cvt_pk_bf16_f32 v238, v10, v11
	v_cvt_pk_bf16_f32 v239, v14, v15
	v_cvt_pk_bf16_f32 v240, v4, v5
	v_cvt_pk_bf16_f32 v241, v8, v9
	v_cvt_pk_bf16_f32 v242, v12, v13
	v_cvt_pk_bf16_f32 v243, v18, v19
	v_cvt_pk_bf16_f32 v244, v20, v21
	v_cvt_pk_bf16_f32 v245, v24, v25
	v_cvt_pk_bf16_f32 v246, v28, v29
	v_cvt_pk_bf16_f32 v247, v36, v37
	v_cvt_pk_bf16_f32 v248, v22, v23
	v_cvt_pk_bf16_f32 v249, v26, v27
	v_cvt_pk_bf16_f32 v250, v30, v31
	v_cvt_pk_bf16_f32 v251, v16, v17
	v_lshrrev_b32_e32 v2, 2, v216
	v_and_b32_e32 v2, 8, v2
	v_add_co_u32_e32 v34, vcc, v2, v34
	s_nop 1
	v_addc_co_u32_e32 v35, vcc, 0, v35, vcc
	s_nop 1
	v_permlane32_swap_b32_e32 v236, v238
	v_permlane32_swap_b32_e32 v237, v239
	v_permlane32_swap_b32_e32 v240, v242
	v_permlane32_swap_b32_e32 v241, v243
	v_permlane32_swap_b32_e32 v244, v246
	v_permlane32_swap_b32_e32 v245, v247
	v_permlane32_swap_b32_e32 v248, v250
	v_permlane32_swap_b32_e32 v249, v251
	global_store_dwordx4 v[34:35], v[236:239], off
	global_store_dwordx4 v[34:35], v[240:243], off offset:64
	global_store_dwordx4 v[34:35], v[244:247], off offset:32
	global_store_dwordx4 v[34:35], v[248:251], off offset:96
	s_mov_b64 s[38:39], 0
	s_branch .LBB0_96
